# gMLP units: LDS tile double-buffered across units so the barrier guarding the previous unit's LDS reads runs only for the first gMLP unit after attention (on v85)
# speedup vs baseline: 1.0043x; 1.0029x over previous
; __global__ void __launch_bounds__(NT, 2) fwd_mega(Args A) {
;     ...
; #pragma unroll 1
;     for (int u = vcu2; u < 1536; u += G) {
;         if (u < 512) attn_unit(PROJ, ws, lds, u);
;         else gmlp_unit(PROJ, ws, lds, u - 512);
.LBB0_594:
	s_add_u32 s10, s28, 0x9900000
	s_addc_u32 s11, s29, 0
	s_add_u32 s20, s28, 0x40000
	s_addc_u32 s21, s29, 0
	s_cmpk_gt_i32 s96, 0x5ff
	s_cbranch_scc1 .LBB0_621
	s_add_u32 s42, s28, 0x1c0000
	s_addc_u32 s43, s29, 0
	s_add_u32 s47, s28, 0x200800
	s_addc_u32 s53, s29, 0
	v_mbcnt_hi_u32_b32 v167, -1, v161
	s_add_u32 s58, s28, 0x201800
	v_and_b32_e32 v0, 64, v167
	s_addc_u32 s59, s29, 0
	s_mov_b32 s45, 0
	v_mov_b32_e32 v163, 0
	s_movk_i32 s60, 0x1c00
	s_mov_b32 s46, 0x3a800000
	s_mov_b32 s61, 0xf800000
	v_mov_b32_e32 v166, 0x260
	s_movk_i32 s62, 0x120
	s_mov_b64 s[48:49], 0x9900800
	s_mov_b32 s63, 0x9900000
	s_movk_i32 s64, 0x110
	s_add_i32 s65, 0, 0x11000
	s_add_i32 s66, 0, 0x19800
	s_mov_b32 s67, 0xf149f2ca
	v_xor_b32_e32 v168, 16, v167
	v_add_u32_e32 v169, 64, v0
	v_xor_b32_e32 v170, 32, v167
	v_mov_b32_e32 v171, 0xf149f2ca
	s_mov_b32 s68, s96
	s_mov_b32 s75, 0
	s_mov_b32 s76, 1
	s_branch .LBB0_598

; #define LAS __attribute__((address_space(3)))
; __device__ __forceinline__ void gmlp_unit(const bf16* proj, unsigned char* ws, LAS unsigned char* lds, int gu) {
;     ...
;     const int gb = gu >> 3, h = gu & 7, tok0 = gb * 128, fr = lane & 15, fq = lane >> 4;
;     LAS unsigned char* VN = lds;
;     const int c = tid & 15, r0 = tid >> 4;
;     v4u raw[4]; f32x2 stv[4];
;     tile_ld(raw, proj, tok0, C_VG + h * 128, tid);
; #pragma unroll
;     for (int p = 0; p < 4; ++p) stv[p] = *(const f32x2*)(lnstat + 2 * (tok0 + r0 + 32 * p));
;     const f32x4 g0 = *(const f32x4*)(par + PAR_GV + h * 128 + 8 * c), g1 = *(const f32x4*)(par + PAR_GV + h * 128 + 8 * c + 4);
;     const f32x4 b0 = *(const f32x4*)(par + PAR_BV + h * 128 + 8 * c), b1 = *(const f32x4*)(par + PAR_BV + h * 128 + 8 * c + 4);
;     bf16x8 wf[4];
; #pragma unroll
;     for (int s = 0; s < 4; ++s) wf[s] = *(const bf16x8*)(wsp + ((size_t)(h * 128 + 16 * wave + fr) * 128 + 32 * s + 8 * fq));
;     const int tok = tok0 + 16 * wave + fr; const float bsp = par[PAR_BSP + h * 128 + 16 * wave + fr];
;     const bf16* urow = proj + (size_t)tok * INW + C_U + h * 128 + 4 * fq; bf16* orow = mix + (size_t)tok * D + 1024 + h * 128 + 4 * fq;
;     v2u uw[8];
; #pragma unroll
;     for (int ct = 0; ct < 8; ++ct) uw[ct] = *(const v2u*)(urow + 16 * ct);
;     __syncthreads();
; #pragma unroll
;     for (int p = 0; p < 4; ++p) {
;         const float mu = stv[p][0] * (1.0f / 1024.0f), var = fmaxf(stv[p][1] * (1.0f / 1024.0f) - mu * mu, 0.f), rstd = 1.0f / sqrtf(var + pg8::EPSN);
.LBB0_600:
	s_add_i32 s0, s68, 0xfffffe00
	v_mov_b32_e32 v41, v160
	s_lshl_b32 s1, s0, 4
	s_and_b32 s4, s1, 0x3f80
	v_ashrrev_i32_e32 v76, 4, v41
	v_add_u32_e32 v10, s4, v76
	v_lshlrev_b32_e32 v0, 1, v10
	s_waitcnt lgkmcnt(0)
	v_ashrrev_i32_e32 v1, 31, v0
	v_lshl_add_u64 v[0:1], v[0:1], 2, s[28:29]
	global_load_dwordx2 v[8:9], v[0:1], off
	s_lshl_b32 s0, s0, 7
	s_and_b32 s13, s0, 0x380
	s_add_i32 s50, s13, 0xa00
	global_load_dwordx2 v[70:71], v[0:1], off offset:256
	global_load_dwordx2 v[72:73], v[0:1], off offset:512
	global_load_dwordx2 v[58:59], v[0:1], off offset:768
	s_lshl_b32 s0, s50, 1
	v_lshlrev_b32_e32 v2, 4, v41
	s_add_u32 s0, s26, s0
	v_and_b32_e32 v162, 0xf0, v2
	s_addc_u32 s1, s27, 0
	s_lshl_b32 s44, s13, 2
	v_lshl_add_u64 v[6:7], s[0:1], 0, v[162:163]
	s_add_u32 s0, s47, s44
	v_and_b32_e32 v78, 15, v41
	v_add_u32_e32 v11, 32, v10
	v_add_u32_e32 v12, 64, v10
	v_add_u32_e32 v15, 0x60, v10
	v_mad_i64_i32 v[0:1], s[2:3], v10, s60, v[6:7]
	s_addc_u32 s1, s53, 0
	v_lshlrev_b32_e32 v14, 5, v78
	v_mad_i64_i32 v[10:11], s[2:3], v11, s60, v[6:7]
	v_mad_i64_i32 v[12:13], s[2:3], v12, s60, v[6:7]
	v_mad_i64_i32 v[6:7], s[2:3], v15, s60, v[6:7]
	global_load_dwordx4 v[62:65], v[0:1], off
	global_load_dwordx4 v[66:69], v[10:11], off
	global_load_dwordx4 v[36:39], v[12:13], off
	global_load_dwordx4 v[32:35], v[6:7], off
	global_load_dwordx4 v[16:19], v14, s[0:1] offset:16
	global_load_dwordx4 v[28:31], v14, s[0:1]
	s_add_u32 s0, s58, s44
	s_addc_u32 s1, s59, 0
	global_load_dwordx4 v[20:23], v14, s[0:1] offset:16
	global_load_dwordx4 v[24:27], v14, s[0:1]
	v_readfirstlane_b32 s5, v41
	s_ashr_i32 s2, s5, 2
	s_and_b32 s0, s2, -16
	s_add_i32 s2, s0, s4
	v_or_b32_e32 v40, s2, v78
	s_add_i32 s1, s0, s13
	s_add_i32 s0, s0, s50
	v_or_b32_e32 v0, s1, v78
	v_or_b32_e32 v6, s0, v78
	v_mov_b64_e32 v[4:5], s[26:27]
	v_ashrrev_i32_e32 v1, 31, v0
	v_bfe_u32 v60, v41, 4, 2
	s_lshl_b32 s44, s13, 1
	v_mad_i64_i32 v[4:5], s[0:1], v40, s60, v[4:5]
	v_lshlrev_b64 v[0:1], 8, v[0:1]
	v_mov_b32_e32 v3, v163
	v_lshlrev_b32_e32 v2, 4, v60
	v_lshlrev_b32_e32 v162, 3, v60
	v_ashrrev_i32_e32 v7, 31, v6
	v_lshl_add_u64 v[4:5], v[4:5], 0, s[44:45]
	v_lshl_add_u64 v[0:1], s[42:43], 0, v[0:1]
	v_lshl_add_u64 v[6:7], v[6:7], 2, s[40:41]
	v_lshl_add_u64 v[4:5], v[4:5], 0, v[162:163]
	v_lshl_add_u64 v[10:11], v[0:1], 0, v[2:3]
	global_load_dword v61, v[6:7], off
	global_load_dwordx2 v[56:57], v[4:5], off offset:3072
	global_load_dwordx2 v[54:55], v[4:5], off offset:3104
	global_load_dwordx2 v[52:53], v[4:5], off offset:3136
	global_load_dwordx2 v[50:51], v[4:5], off offset:3168
	global_load_dwordx2 v[48:49], v[4:5], off offset:3200
	global_load_dwordx2 v[46:47], v[4:5], off offset:3232
	global_load_dwordx2 v[44:45], v[4:5], off offset:3264
	global_load_dwordx2 v[42:43], v[4:5], off offset:3296
	global_load_dwordx4 v[0:3], v[10:11], off
	s_nop 0
	global_load_dwordx4 v[4:7], v[10:11], off offset:64
	v_lshlrev_b32_e32 v78, 4, v78
	v_mul_lo_u32 v76, v76, s62
	v_add3_u32 v76, s75, v78, v76
	v_lshlrev_b32_e32 v77, 3, v41
	s_waitcnt vmcnt(22)
	v_pk_mul_f32 v[74:75], v[8:9], s[46:47] op_sel_hi:[1,0]
	s_nop 0
	v_fma_f32 v8, -v74, v74, v75
	v_max_f32_e32 v8, 0, v8
	v_add_f32_e32 v8, 0x358637bd, v8
	v_mul_f32_e32 v9, 0x4f800000, v8
	v_cmp_gt_f32_e32 vcc, s61, v8
	s_waitcnt vmcnt(21)
	v_pk_mul_f32 v[70:71], v[70:71], s[46:47] op_sel_hi:[1,0]
	s_waitcnt vmcnt(19)
	v_pk_mul_f32 v[58:59], v[58:59], s[46:47] op_sel_hi:[1,0]
	v_cndmask_b32_e32 v75, v8, v9, vcc
	v_sqrt_f32_e32 v79, v75
	v_fma_f32 v71, -v70, v70, v71
	v_max_f32_e32 v71, 0, v71
	v_add_f32_e32 v71, 0x358637bd, v71
	v_add_u32_e32 v80, -1, v79
	v_fma_f32 v81, -v80, v79, v75
	v_cmp_ge_f32_e64 s[2:3], 0, v81
	v_add_u32_e32 v81, 1, v79
	global_load_dwordx4 v[12:15], v[10:11], off offset:128
	s_nop 0
	global_load_dwordx4 v[8:11], v[10:11], off offset:192
	v_cndmask_b32_e64 v80, v79, v80, s[2:3]
	v_fma_f32 v79, -v81, v79, v75
	v_cmp_lt_f32_e64 s[2:3], 0, v79
	s_cmp_eq_u32 s76, 0
	s_cbranch_scc1 .Lgm_nobar
	s_barrier
.Lgm_nobar:
	s_nop 0
	v_cndmask_b32_e64 v79, v80, v81, s[2:3]
	v_mul_f32_e32 v80, 0x37800000, v79
	v_cndmask_b32_e32 v79, v79, v80, vcc
	v_cmp_class_f32_e32 vcc, v75, v166
	v_fma_f32 v59, -v58, v58, v59
	s_nop 0
	v_cndmask_b32_e32 v75, v79, v75, vcc
	v_div_scale_f32 v79, s[0:1], v75, v75, 1.0
	v_rcp_f32_e32 v80, v79
	v_max_f32_e32 v59, 0, v59
	v_add_f32_e32 v59, 0x358637bd, v59
	v_fma_f32 v81, -v79, v80, 1.0
	v_fmac_f32_e32 v80, v81, v80
	v_div_scale_f32 v81, vcc, 1.0, v75, 1.0
	v_mul_f32_e32 v82, v81, v80
	v_fma_f32 v83, -v79, v82, v81
	v_fmac_f32_e32 v82, v83, v80
	v_fma_f32 v79, -v79, v82, v81
	v_div_fmas_f32 v79, v79, v80, v82
	v_div_fixup_f32 v75, v79, v75, 1.0
	s_waitcnt vmcnt(20)
	v_lshlrev_b32_e32 v79, 16, v62
	v_and_b32_e32 v62, 0xffff0000, v62
	v_lshlrev_b32_e32 v80, 16, v63
	v_and_b32_e32 v63, 0xffff0000, v63
	v_lshlrev_b32_e32 v81, 16, v64
	v_and_b32_e32 v64, 0xffff0000, v64
	v_lshlrev_b32_e32 v82, 16, v65
	v_and_b32_e32 v65, 0xffff0000, v65
	v_sub_f32_e32 v79, v79, v74
	v_sub_f32_e32 v81, v81, v74
	v_sub_f32_e32 v62, v62, v74
	v_sub_f32_e32 v64, v64, v74
	v_sub_f32_e32 v80, v80, v74
	v_sub_f32_e32 v82, v82, v74
	v_sub_f32_e32 v63, v63, v74
	v_sub_f32_e32 v65, v65, v74
	v_mul_f32_e32 v74, 0x4f800000, v71
	v_cmp_gt_f32_e32 vcc, s61, v71
	v_mul_f32_e32 v79, v79, v75
	v_mul_f32_e32 v62, v62, v75
	v_cndmask_b32_e32 v71, v71, v74, vcc
	v_sqrt_f32_e32 v74, v71
	s_waitcnt vmcnt(13)
; #define LAS __attribute__((address_space(3)))
; __device__ __forceinline__ unsigned pk2(float lo, float hi) { return pg8::cvt_pk_bf16(lo, hi); }
; __device__ __forceinline__ void gmlp_unit(const bf16* proj, unsigned char* ws, LAS unsigned char* lds, int gu) {
;     ...
;     for (int p = 0; p < 4; ++p) {
;         const float mu = stv[p][0] * (1.0f / 1024.0f), var = fmaxf(stv[p][1] * (1.0f / 1024.0f) - mu * mu, 0.f), rstd = 1.0f / sqrtf(var + pg8::EPSN);
;         float v[8];
;         v[0] = bflo(raw[p].x); v[1] = bfhi(raw[p].x); v[2] = bflo(raw[p].y); v[3] = bfhi(raw[p].y); v[4] = bflo(raw[p].z); v[5] = bfhi(raw[p].z); v[6] = bflo(raw[p].w); v[7] = bfhi(raw[p].w);
; #pragma unroll
;         for (int e = 0; e < 4; ++e) { v[e] = (v[e] - mu) * rstd * g0[e] + b0[e]; v[4 + e] = (v[4 + e] - mu) * rstd * g1[e] + b1[e]; }
;         v4u o; o.x = pk2(v[0], v[1]); o.y = pk2(v[2], v[3]); o.z = pk2(v[4], v[5]); o.w = pk2(v[6], v[7]);
;         *(LAS v4u*)(VN + (r0 + 32 * p) * V_STRIDE + c * 16) = o;
;     }
;     __syncthreads();
	v_fma_f32 v79, v28, v79, v24
	v_mul_f32_e32 v81, v81, v75
	v_fma_f32 v62, v29, v62, v25
	v_mul_f32_e32 v64, v64, v75
	v_mul_f32_e32 v80, v80, v75
	v_mul_f32_e32 v82, v82, v75
	v_mul_f32_e32 v63, v63, v75
	v_mul_f32_e32 v65, v65, v75
	v_add_u32_e32 v75, -1, v74
	v_cvt_pk_bf16_f32 v62, v79, v62
	v_fma_f32 v79, -v75, v74, v71
	v_cmp_ge_f32_e64 s[2:3], 0, v79
	v_add_u32_e32 v79, 1, v74
	v_fma_f32 v64, v17, v64, v21
	v_cndmask_b32_e64 v75, v74, v75, s[2:3]
	v_fma_f32 v74, -v79, v74, v71
	v_cmp_lt_f32_e64 s[2:3], 0, v74
	v_fma_f32 v63, v31, v63, v27
	v_fma_f32 v65, v19, v65, v23
	v_cndmask_b32_e64 v74, v75, v79, s[2:3]
	v_mul_f32_e32 v75, 0x37800000, v74
	v_cndmask_b32_e32 v74, v74, v75, vcc
	v_cmp_class_f32_e32 vcc, v71, v166
	v_fma_f32 v81, v16, v81, v20
	v_fma_f32 v80, v30, v80, v26
	v_cndmask_b32_e32 v71, v74, v71, vcc
	v_div_scale_f32 v74, s[0:1], v71, v71, 1.0
	v_rcp_f32_e32 v75, v74
	v_fma_f32 v82, v18, v82, v22
	v_cvt_pk_bf16_f32 v63, v80, v63
	v_cvt_pk_bf16_f32 v64, v81, v64
	v_cvt_pk_bf16_f32 v65, v82, v65
	ds_write_b128 v76, v[62:65]
	v_fma_f32 v62, -v74, v75, 1.0
	v_fmac_f32_e32 v75, v62, v75
	v_div_scale_f32 v62, vcc, 1.0, v71, 1.0
	v_mul_f32_e32 v63, v62, v75
	v_fma_f32 v64, -v74, v63, v62
	v_fmac_f32_e32 v63, v64, v75
	v_fma_f32 v62, -v74, v63, v62
	v_div_fmas_f32 v62, v62, v75, v63
	v_lshlrev_b32_e32 v63, 16, v66
	v_and_b32_e32 v64, 0xffff0000, v66
	v_lshlrev_b32_e32 v65, 16, v67
	v_and_b32_e32 v66, 0xffff0000, v67
	v_lshlrev_b32_e32 v67, 16, v68
	v_div_fixup_f32 v62, v62, v71, 1.0
	v_sub_f32_e32 v67, v67, v70
	v_and_b32_e32 v68, 0xffff0000, v68
	v_mul_f32_e32 v67, v67, v62
	v_fma_f32 v74, v16, v67, v20
	v_sub_f32_e32 v67, v68, v70
	v_lshlrev_b32_e32 v71, 16, v69
	v_mul_f32_e32 v67, v67, v62
	v_sub_f32_e32 v66, v66, v70
	v_and_b32_e32 v69, 0xffff0000, v69
	v_fma_f32 v68, v17, v67, v21
	v_sub_f32_e32 v67, v71, v70
	v_mul_f32_e32 v66, v66, v62
	v_sub_f32_e32 v63, v63, v70
	v_sub_f32_e32 v64, v64, v70
	v_sub_f32_e32 v65, v65, v70
	v_mul_f32_e32 v67, v67, v62
	v_fma_f32 v75, v31, v66, v27
	v_sub_f32_e32 v66, v69, v70
	v_mul_f32_e32 v63, v63, v62
	v_mul_f32_e32 v64, v64, v62
	v_mul_f32_e32 v65, v65, v62
	v_fma_f32 v71, v18, v67, v22
	v_mul_f32_e32 v62, v66, v62
	v_pk_mul_f32 v[66:67], v[72:73], s[46:47] op_sel_hi:[1,0]
	v_fma_f32 v64, v29, v64, v25
	v_fma_f32 v67, -v66, v66, v67
	v_max_f32_e32 v67, 0, v67
	v_add_f32_e32 v67, 0x358637bd, v67
	v_mul_f32_e32 v69, 0x4f800000, v67
	v_cmp_gt_f32_e32 vcc, s61, v67
	v_fma_f32 v63, v28, v63, v24
	v_fma_f32 v65, v30, v65, v26
	v_cndmask_b32_e32 v67, v67, v69, vcc
	v_sqrt_f32_e32 v69, v67
	v_fma_f32 v70, v19, v62, v23
	v_cvt_pk_bf16_f32 v62, v63, v64
	v_cvt_pk_bf16_f32 v63, v65, v75
	v_add_u32_e32 v64, -1, v69
	v_fma_f32 v65, -v64, v69, v67
	v_cmp_ge_f32_e64 s[2:3], 0, v65
	v_add_u32_e32 v65, 1, v69
	s_nop 0
	v_cndmask_b32_e64 v64, v69, v64, s[2:3]
	v_fma_f32 v69, -v65, v69, v67
	v_cmp_lt_f32_e64 s[2:3], 0, v69
	s_nop 1
	v_cndmask_b32_e64 v64, v64, v65, s[2:3]
	v_mul_f32_e32 v65, 0x37800000, v64
	v_cndmask_b32_e32 v64, v64, v65, vcc
	v_cmp_class_f32_e32 vcc, v67, v166
	s_nop 1
	v_cndmask_b32_e32 v67, v64, v67, vcc
	v_div_scale_f32 v69, s[0:1], v67, v67, 1.0
	v_rcp_f32_e32 v72, v69
	v_cvt_pk_bf16_f32 v64, v74, v68
	v_cvt_pk_bf16_f32 v65, v71, v70
	ds_write_b128 v76, v[62:65] offset:9216
	v_fma_f32 v62, -v69, v72, 1.0
	v_fmac_f32_e32 v72, v62, v72
	v_div_scale_f32 v62, vcc, 1.0, v67, 1.0
	v_mul_f32_e32 v63, v62, v72
	v_fma_f32 v64, -v69, v63, v62
	v_fmac_f32_e32 v63, v64, v72
	v_fma_f32 v62, -v69, v63, v62
	v_div_fmas_f32 v62, v62, v72, v63
	v_div_fixup_f32 v62, v62, v67, 1.0
	v_lshlrev_b32_e32 v63, 16, v36
	v_and_b32_e32 v36, 0xffff0000, v36
	v_lshlrev_b32_e32 v64, 16, v37
	v_and_b32_e32 v37, 0xffff0000, v37
	v_lshlrev_b32_e32 v65, 16, v38
	v_and_b32_e32 v38, 0xffff0000, v38
	v_lshlrev_b32_e32 v67, 16, v39
	v_and_b32_e32 v39, 0xffff0000, v39
	v_sub_f32_e32 v63, v63, v66
	v_sub_f32_e32 v65, v65, v66
	v_sub_f32_e32 v36, v36, v66
	v_sub_f32_e32 v38, v38, v66
	v_sub_f32_e32 v64, v64, v66
	v_sub_f32_e32 v67, v67, v66
	v_sub_f32_e32 v37, v37, v66
	v_sub_f32_e32 v39, v39, v66
	v_mul_f32_e32 v63, v63, v62
	v_mul_f32_e32 v65, v65, v62
	v_mul_f32_e32 v36, v36, v62
	v_mul_f32_e32 v38, v38, v62
	v_mul_f32_e32 v64, v64, v62
	v_mul_f32_e32 v67, v67, v62
	v_mul_f32_e32 v37, v37, v62
	v_mul_f32_e32 v39, v39, v62
	v_mul_f32_e32 v62, 0x4f800000, v59
	v_cmp_gt_f32_e32 vcc, s61, v59
	v_fma_f32 v63, v28, v63, v24
	v_fma_f32 v36, v29, v36, v25
	v_cndmask_b32_e32 v59, v59, v62, vcc
	v_sqrt_f32_e32 v62, v59
	v_fma_f32 v64, v30, v64, v26
	v_fma_f32 v37, v31, v37, v27
	v_cvt_pk_bf16_f32 v36, v63, v36
	v_add_u32_e32 v63, -1, v62
	v_cvt_pk_bf16_f32 v37, v64, v37
	v_fma_f32 v64, -v63, v62, v59
	v_cmp_ge_f32_e64 s[2:3], 0, v64
	v_add_u32_e32 v64, 1, v62
	v_fma_f32 v38, v17, v38, v21
	v_cndmask_b32_e64 v63, v62, v63, s[2:3]
	v_fma_f32 v62, -v64, v62, v59
	v_cmp_lt_f32_e64 s[2:3], 0, v62
	v_fma_f32 v39, v19, v39, v23
	v_fma_f32 v65, v16, v65, v20
	v_cndmask_b32_e64 v62, v63, v64, s[2:3]
	v_mul_f32_e32 v63, 0x37800000, v62
	v_cndmask_b32_e32 v62, v62, v63, vcc
	v_cmp_class_f32_e32 vcc, v59, v166
	v_fma_f32 v67, v18, v67, v22
	v_cvt_pk_bf16_f32 v38, v65, v38
	v_cvt_pk_bf16_f32 v39, v67, v39
	ds_write_b128 v76, v[36:39] offset:18432
	v_cndmask_b32_e32 v59, v62, v59, vcc
	v_div_scale_f32 v62, s[0:1], v59, v59, 1.0
	v_rcp_f32_e32 v63, v62
	v_lshlrev_b32_e32 v39, 16, v34
	v_and_b32_e32 v34, 0xffff0000, v34
	v_fma_f32 v36, -v62, v63, 1.0
	v_fmac_f32_e32 v63, v36, v63
	v_div_scale_f32 v36, vcc, 1.0, v59, 1.0
	v_mul_f32_e32 v37, v36, v63
	v_fma_f32 v38, -v62, v37, v36
	v_fmac_f32_e32 v37, v38, v63
	v_fma_f32 v36, -v62, v37, v36
	v_div_fmas_f32 v36, v36, v63, v37
	v_lshlrev_b32_e32 v37, 16, v32
	v_div_fixup_f32 v36, v36, v59, 1.0
	v_sub_f32_e32 v37, v37, v58
	v_mul_f32_e32 v37, v37, v36
	v_fma_f32 v24, v28, v37, v24
	v_sub_f32_e32 v28, v39, v58
	v_and_b32_e32 v32, 0xffff0000, v32
	v_mul_f32_e32 v28, v28, v36
	v_fma_f32 v20, v16, v28, v20
	v_sub_f32_e32 v16, v32, v58
	v_mul_f32_e32 v16, v16, v36
	v_fma_f32 v16, v29, v16, v25
	v_sub_f32_e32 v25, v34, v58
	v_lshlrev_b32_e32 v59, 16, v35
	v_mul_f32_e32 v25, v25, v36
	v_fma_f32 v21, v17, v25, v21
	v_sub_f32_e32 v25, v59, v58
	v_lshlrev_b32_e32 v38, 16, v33
	v_and_b32_e32 v33, 0xffff0000, v33
	v_mul_f32_e32 v25, v25, v36
	v_fma_f32 v22, v18, v25, v22
	v_sub_f32_e32 v18, v33, v58
	v_and_b32_e32 v35, 0xffff0000, v35
	v_sub_f32_e32 v17, v38, v58
	v_mul_f32_e32 v18, v18, v36
	v_mul_f32_e32 v17, v17, v36
	v_fmac_f32_e32 v27, v31, v18
	v_sub_f32_e32 v18, v35, v58
	v_fma_f32 v17, v30, v17, v26
	v_mul_f32_e32 v18, v18, v36
	v_cvt_pk_bf16_f32 v16, v24, v16
	v_fmac_f32_e32 v23, v19, v18
	v_cvt_pk_bf16_f32 v17, v17, v27
	v_cvt_pk_bf16_f32 v18, v20, v21
	v_cvt_pk_bf16_f32 v19, v22, v23
	ds_write_b128 v76, v[16:19] offset:27648
	v_bfe_u32 v16, v41, 2, 2
	v_or_b32_e32 v16, v162, v16
	v_and_b32_e32 v17, 24, v77
	v_mul_u32_u24_e32 v16, 0x120, v16
	v_add3_u32 v41, s75, v17, v16
	s_xor_b32 s75, s75, 0x10000
	s_mov_b32 s76, 0
	s_nop 0
	s_waitcnt lgkmcnt(0)
	s_barrier
; #define LAS __attribute__((address_space(3)))
; __device__ __forceinline__ void gmlp_unit(const bf16* proj, unsigned char* ws, LAS unsigned char* lds, int gu) {
;     ...
;     f32x4 acc[8];
; #pragma unroll
;     for (int ct = 0; ct < 8; ++ct) {
;         acc[ct] = (f32x4){0.f, 0.f, 0.f, 0.f};
; #pragma unroll
;         for (int s = 0; s < 4; ++s) {
;             const LAS unsigned char* p0 = VN + (32 * s + 8 * fq + (fr >> 2)) * V_STRIDE + (16 * ct + 4 * (fr & 3)) * 2;
;             const bf16x8 vf = tr_frag(p0, p0 + 4 * V_STRIDE);
;             acc[ct] = __builtin_amdgcn_mfma_f32_16x16x32_bf16(vf, wf[s], acc[ct], 0, 0, 0);
;         }
;     }
	ds_read_b64_tr_b16 v[18:19], v41 offset:1152
	ds_read_b64_tr_b16 v[16:17], v41
	ds_read_b64_tr_b16 v[20:21], v41 offset:9216
	ds_read_b64_tr_b16 v[22:23], v41 offset:10368
	ds_read_b64_tr_b16 v[24:25], v41 offset:32
	ds_read_b64_tr_b16 v[28:29], v41 offset:64
	ds_read_b64_tr_b16 v[32:33], v41 offset:96
	ds_read_b64_tr_b16 v[26:27], v41 offset:1184
	ds_read_b64_tr_b16 v[30:31], v41 offset:1216
	ds_read_b64_tr_b16 v[34:35], v41 offset:1248
	s_waitcnt vmcnt(3) lgkmcnt(2)
	v_mfma_f32_16x16x32_bf16 v[24:27], v[24:27], v[0:3], 0
	ds_read_b64_tr_b16 v[36:37], v41 offset:9248
	ds_read_b64_tr_b16 v[62:63], v41 offset:9280
	ds_read_b64_tr_b16 v[66:67], v41 offset:9312
	ds_read_b64_tr_b16 v[38:39], v41 offset:10400
	ds_read_b64_tr_b16 v[64:65], v41 offset:10432
	ds_read_b64_tr_b16 v[68:69], v41 offset:10464
	v_mfma_f32_16x16x32_bf16 v[16:19], v[16:19], v[0:3], 0
	s_waitcnt vmcnt(2) lgkmcnt(2)
	v_mfma_f32_16x16x32_bf16 v[24:27], v[36:39], v[4:7], v[24:27]
	v_mfma_f32_16x16x32_bf16 v[16:19], v[20:23], v[4:7], v[16:19]
	ds_read_b64_tr_b16 v[20:21], v41 offset:18432
	ds_read_b64_tr_b16 v[22:23], v41 offset:19584
	ds_read_b64_tr_b16 v[70:71], v41 offset:27648
	ds_read_b64_tr_b16 v[72:73], v41 offset:28800
	ds_read_b64_tr_b16 v[74:75], v41 offset:18464
	ds_read_b64_tr_b16 v[78:79], v41 offset:18496
	ds_read_b64_tr_b16 v[82:83], v41 offset:18528
	ds_read_b64_tr_b16 v[76:77], v41 offset:19616
	ds_read_b64_tr_b16 v[80:81], v41 offset:19648
	ds_read_b64_tr_b16 v[84:85], v41 offset:19680
	s_waitcnt vmcnt(1) lgkmcnt(2)
	v_mfma_f32_16x16x32_bf16 v[24:27], v[74:77], v[12:15], v[24:27]
	v_mfma_f32_16x16x32_bf16 v[16:19], v[20:23], v[12:15], v[16:19]
	ds_read_b64_tr_b16 v[20:21], v41 offset:27680
	ds_read_b64_tr_b16 v[86:87], v41 offset:27712
	ds_read_b64_tr_b16 v[90:91], v41 offset:27744
	ds_read_b64_tr_b16 v[22:23], v41 offset:28832
	ds_read_b64_tr_b16 v[88:89], v41 offset:28864
	ds_read_b64_tr_b16 v[92:93], v41 offset:28896
	s_waitcnt vmcnt(0) lgkmcnt(2)
	v_mfma_f32_16x16x32_bf16 v[20:23], v[20:23], v[8:11], v[24:27]
	v_mfma_f32_16x16x32_bf16 v[24:27], v[28:31], v[0:3], 0
	v_mfma_f32_16x16x32_bf16 v[28:31], v[32:35], v[0:3], 0
	v_mfma_f32_16x16x32_bf16 v[16:19], v[70:73], v[8:11], v[16:19]
	v_mfma_f32_16x16x32_bf16 v[24:27], v[62:65], v[4:7], v[24:27]
	v_mfma_f32_16x16x32_bf16 v[28:31], v[66:69], v[4:7], v[28:31]
	ds_read_b64_tr_b16 v[32:33], v41 offset:128
	ds_read_b64_tr_b16 v[34:35], v41 offset:1280
	ds_read_b64_tr_b16 v[36:37], v41 offset:9344
	ds_read_b64_tr_b16 v[38:39], v41 offset:10496
	ds_read_b64_tr_b16 v[62:63], v41 offset:160
	ds_read_b64_tr_b16 v[66:67], v41 offset:192
	ds_read_b64_tr_b16 v[70:71], v41 offset:224
	ds_read_b64_tr_b16 v[64:65], v41 offset:1312
	ds_read_b64_tr_b16 v[68:69], v41 offset:1344
	ds_read_b64_tr_b16 v[72:73], v41 offset:1376
	s_waitcnt lgkmcnt(2)
	v_mfma_f32_16x16x32_bf16 v[62:65], v[62:65], v[0:3], 0
	v_mfma_f32_16x16x32_bf16 v[24:27], v[78:81], v[12:15], v[24:27]
	v_mfma_f32_16x16x32_bf16 v[28:31], v[82:85], v[12:15], v[28:31]
	ds_read_b64_tr_b16 v[74:75], v41 offset:9376
	ds_read_b64_tr_b16 v[78:79], v41 offset:9408
	ds_read_b64_tr_b16 v[82:83], v41 offset:9440
	ds_read_b64_tr_b16 v[76:77], v41 offset:10528
	ds_read_b64_tr_b16 v[80:81], v41 offset:10560
	ds_read_b64_tr_b16 v[84:85], v41 offset:10592
	v_mfma_f32_16x16x32_bf16 v[32:35], v[32:35], v[0:3], 0
	s_waitcnt lgkmcnt(2)
	v_mfma_f32_16x16x32_bf16 v[62:65], v[74:77], v[4:7], v[62:65]
	v_mfma_f32_16x16x32_bf16 v[24:27], v[86:89], v[8:11], v[24:27]
	v_mfma_f32_16x16x32_bf16 v[28:31], v[90:93], v[8:11], v[28:31]
	v_mfma_f32_16x16x32_bf16 v[32:35], v[36:39], v[4:7], v[32:35]
	ds_read_b64_tr_b16 v[36:37], v41 offset:18560
	ds_read_b64_tr_b16 v[38:39], v41 offset:19712
	ds_read_b64_tr_b16 v[86:87], v41 offset:27776
	ds_read_b64_tr_b16 v[88:89], v41 offset:28928
	ds_read_b64_tr_b16 v[90:91], v41 offset:18592
	ds_read_b64_tr_b16 v[94:95], v41 offset:18624
	ds_read_b64_tr_b16 v[98:99], v41 offset:18656
	ds_read_b64_tr_b16 v[92:93], v41 offset:19744
	ds_read_b64_tr_b16 v[96:97], v41 offset:19776
	ds_read_b64_tr_b16 v[100:101], v41 offset:19808
	s_waitcnt lgkmcnt(2)
	v_mfma_f32_16x16x32_bf16 v[62:65], v[90:93], v[12:15], v[62:65]
	v_mfma_f32_16x16x32_bf16 v[32:35], v[36:39], v[12:15], v[32:35]
	ds_read_b64_tr_b16 v[36:37], v41 offset:27808
	ds_read_b64_tr_b16 v[102:103], v41 offset:27840
	ds_read_b64_tr_b16 v[106:107], v41 offset:27872
	ds_read_b64_tr_b16 v[38:39], v41 offset:28960
	ds_read_b64_tr_b16 v[104:105], v41 offset:28992
	ds_read_b64_tr_b16 v[108:109], v41 offset:29024
	v_ashrrev_i32_e32 v41, 31, v40
	s_waitcnt lgkmcnt(2)
	v_mfma_f32_16x16x32_bf16 v[36:39], v[36:39], v[8:11], v[62:65]
	v_mfma_f32_16x16x32_bf16 v[62:65], v[66:69], v[0:3], 0
	v_mfma_f32_16x16x32_bf16 v[0:3], v[70:73], v[0:3], 0
	v_mfma_f32_16x16x32_bf16 v[62:65], v[78:81], v[4:7], v[62:65]
	v_mfma_f32_16x16x32_bf16 v[0:3], v[82:85], v[4:7], v[0:3]
	v_lshlrev_b64 v[4:5], 12, v[40:41]
	v_lshl_add_u64 v[4:5], s[28:29], 0, v[4:5]
	v_lshl_add_u64 v[4:5], v[4:5], 0, s[44:45]
	v_mfma_f32_16x16x32_bf16 v[62:65], v[94:97], v[12:15], v[62:65]
	v_lshl_add_u64 v[4:5], v[4:5], 0, v[162:163]
	v_lshl_add_u64 v[6:7], v[4:5], 0, s[48:49]
	v_add_co_u32_e32 v4, vcc, s63, v4
	v_mfma_f32_16x16x32_bf16 v[0:3], v[98:101], v[12:15], v[0:3]
	v_add_f32_e32 v12, v61, v19
	v_addc_co_u32_e32 v5, vcc, 0, v5, vcc
	v_mfma_f32_16x16x32_bf16 v[32:35], v[86:89], v[8:11], v[32:35]
	v_cmp_lt_i32_e32 vcc, v168, v169
	s_waitcnt lgkmcnt(1)
	v_mfma_f32_16x16x32_bf16 v[62:65], v[102:105], v[8:11], v[62:65]
	s_waitcnt lgkmcnt(0)
; __device__ __forceinline__ unsigned pk2(float lo, float hi) { return pg8::cvt_pk_bf16(lo, hi); }
; __device__ __forceinline__ void gmlp_unit(const bf16* proj, unsigned char* ws, LAS unsigned char* lds, int gu) {
;     ...
;     float ss = 0.f;
; #pragma unroll
;     for (int ct = 0; ct < 8; ++ct) {
;         const float o0 = bflo(uw[ct].x) * (acc[ct][0] + bsp), o1 = bfhi(uw[ct].x) * (acc[ct][1] + bsp), o2 = bflo(uw[ct].y) * (acc[ct][2] + bsp), o3 = bfhi(uw[ct].y) * (acc[ct][3] + bsp);
;         ss += (o0 * o0 + o1 * o1) + (o2 * o2 + o3 * o3);
;         v2u w; w.x = pk2(o0, o1); w.y = pk2(o2, o3); *(v2u*)(orow + 16 * ct) = w;
;     }
;     ss += __shfl_xor(ss, 16); ss += __shfl_xor(ss, 32);
;     if (fq == 0) unsafeAtomicAdd(ssmix + (size_t)tok * 2 + 1, ss);
	v_mfma_f32_16x16x32_bf16 v[0:3], v[106:109], v[8:11], v[0:3]
	v_lshlrev_b32_e32 v8, 16, v56
	v_add_f32_e32 v9, v61, v16
	v_mul_f32_e32 v8, v9, v8
	v_and_b32_e32 v9, 0xffff0000, v56
	v_add_f32_e32 v10, v61, v17
	v_mul_f32_e32 v9, v10, v9
	v_lshlrev_b32_e32 v10, 16, v57
	v_add_f32_e32 v11, v61, v18
	v_mul_f32_e32 v10, v11, v10
	v_and_b32_e32 v11, 0xffff0000, v57
	v_mul_f32_e32 v11, v12, v11
	v_mul_f32_e32 v12, v9, v9
	v_fmac_f32_e32 v12, v8, v8
	v_cvt_pk_bf16_f32 v8, v8, v9
	v_cvt_pk_bf16_f32 v9, v10, v11
	global_store_dwordx2 v[4:5], v[8:9], off offset:2048
	v_lshlrev_b32_e32 v4, 16, v54
	v_add_f32_e32 v5, v61, v20
	v_mul_f32_e32 v4, v5, v4
	v_and_b32_e32 v5, 0xffff0000, v54
	v_add_f32_e32 v8, v61, v21
	v_mul_f32_e32 v13, v11, v11
	v_mul_f32_e32 v5, v8, v5
	v_lshlrev_b32_e32 v8, 16, v55
	v_add_f32_e32 v9, v61, v22
	v_fmac_f32_e32 v13, v10, v10
	v_mul_f32_e32 v8, v9, v8
	v_and_b32_e32 v9, 0xffff0000, v55
	v_add_f32_e32 v10, v61, v23
	v_mul_f32_e32 v9, v10, v9
	v_mul_f32_e32 v10, v5, v5
	v_fmac_f32_e32 v10, v4, v4
	v_cvt_pk_bf16_f32 v4, v4, v5
	v_cvt_pk_bf16_f32 v5, v8, v9
	v_mul_f32_e32 v11, v9, v9
	global_store_dwordx2 v[6:7], v[4:5], off offset:32
	v_lshlrev_b32_e32 v4, 16, v52
	v_add_f32_e32 v5, v61, v24
	v_fmac_f32_e32 v11, v8, v8
	v_mul_f32_e32 v4, v5, v4
	v_and_b32_e32 v5, 0xffff0000, v52
	v_add_f32_e32 v8, v61, v25
	v_mul_f32_e32 v5, v8, v5
	v_lshlrev_b32_e32 v8, 16, v53
	v_add_f32_e32 v9, v61, v26
	v_add_f32_e32 v10, v10, v11
	v_mul_f32_e32 v8, v9, v8
	v_and_b32_e32 v9, 0xffff0000, v53
	v_add_f32_e32 v11, v61, v27
	v_mul_f32_e32 v9, v11, v9
	v_mul_f32_e32 v11, v5, v5
	v_add_f32_e32 v12, v12, v13
	v_fmac_f32_e32 v11, v4, v4
	v_cvt_pk_bf16_f32 v4, v4, v5
	v_cvt_pk_bf16_f32 v5, v8, v9
	v_add_f32_e32 v10, v12, v10
	v_mul_f32_e32 v12, v9, v9
	global_store_dwordx2 v[6:7], v[4:5], off offset:64
	v_lshlrev_b32_e32 v4, 16, v50
	v_add_f32_e32 v5, v61, v28
	v_fmac_f32_e32 v12, v8, v8
	v_mul_f32_e32 v4, v5, v4
	v_and_b32_e32 v5, 0xffff0000, v50
	v_add_f32_e32 v8, v61, v29
	v_add_f32_e32 v11, v11, v12
	v_mul_f32_e32 v5, v8, v5
	v_lshlrev_b32_e32 v8, 16, v51
	v_add_f32_e32 v9, v61, v30
	v_add_f32_e32 v10, v10, v11
	v_mul_f32_e32 v8, v9, v8
	v_and_b32_e32 v9, 0xffff0000, v51
	v_add_f32_e32 v11, v61, v31
	v_mul_f32_e32 v9, v11, v9
	v_mul_f32_e32 v11, v5, v5
	v_fmac_f32_e32 v11, v4, v4
	v_cvt_pk_bf16_f32 v4, v4, v5
	v_cvt_pk_bf16_f32 v5, v8, v9
	v_mul_f32_e32 v12, v9, v9
	global_store_dwordx2 v[6:7], v[4:5], off offset:96
	v_lshlrev_b32_e32 v4, 16, v48
	v_add_f32_e32 v5, v61, v32
	v_fmac_f32_e32 v12, v8, v8
	v_mul_f32_e32 v4, v5, v4
	v_and_b32_e32 v5, 0xffff0000, v48
	v_add_f32_e32 v8, v61, v33
	v_add_f32_e32 v11, v11, v12
	v_mul_f32_e32 v5, v8, v5
	v_lshlrev_b32_e32 v8, 16, v49
	v_add_f32_e32 v9, v61, v34
	v_add_f32_e32 v10, v10, v11
	v_mul_f32_e32 v8, v9, v8
	v_and_b32_e32 v9, 0xffff0000, v49
	v_add_f32_e32 v11, v61, v35
	v_mul_f32_e32 v9, v11, v9
	v_mul_f32_e32 v11, v5, v5
	v_fmac_f32_e32 v11, v4, v4
	v_cvt_pk_bf16_f32 v4, v4, v5
	v_cvt_pk_bf16_f32 v5, v8, v9
	v_mul_f32_e32 v12, v9, v9
	global_store_dwordx2 v[6:7], v[4:5], off offset:128
	v_lshlrev_b32_e32 v4, 16, v46
	v_add_f32_e32 v5, v61, v36
	v_fmac_f32_e32 v12, v8, v8
	v_mul_f32_e32 v4, v5, v4
	v_and_b32_e32 v5, 0xffff0000, v46
	v_add_f32_e32 v8, v61, v37
	v_add_f32_e32 v11, v11, v12
	v_mul_f32_e32 v5, v8, v5
	v_lshlrev_b32_e32 v8, 16, v47
	v_add_f32_e32 v9, v61, v38
	v_add_f32_e32 v10, v10, v11
	v_mul_f32_e32 v8, v9, v8
	v_and_b32_e32 v9, 0xffff0000, v47
	v_add_f32_e32 v11, v61, v39
	v_mul_f32_e32 v9, v11, v9
	v_mul_f32_e32 v11, v5, v5
	v_mul_f32_e32 v12, v9, v9
	v_fmac_f32_e32 v11, v4, v4
	v_fmac_f32_e32 v12, v8, v8
	v_add_f32_e32 v11, v11, v12
	v_cvt_pk_bf16_f32 v4, v4, v5
	v_cvt_pk_bf16_f32 v5, v8, v9
	v_lshlrev_b32_e32 v8, 16, v44
	v_add_f32_e32 v9, v61, v62
	v_add_f32_e32 v10, v10, v11
	v_mul_f32_e32 v8, v9, v8
	v_and_b32_e32 v9, 0xffff0000, v44
	v_add_f32_e32 v11, v61, v63
	v_mul_f32_e32 v9, v11, v9
	v_lshlrev_b32_e32 v11, 16, v45
	v_add_f32_e32 v12, v61, v64
	v_mul_f32_e32 v11, v12, v11
	v_and_b32_e32 v12, 0xffff0000, v45
	v_add_f32_e32 v13, v61, v65
	v_mul_f32_e32 v12, v13, v12
	v_mul_f32_e32 v13, v9, v9
	v_mul_f32_e32 v14, v12, v12
	v_fmac_f32_e32 v13, v8, v8
	v_fmac_f32_e32 v14, v11, v11
	v_add_f32_e32 v13, v13, v14
	v_add_f32_e32 v10, v10, v13
	v_lshlrev_b32_e32 v13, 16, v42
	v_add_f32_e32 v0, v61, v0
	v_mul_f32_e32 v13, v0, v13
	v_and_b32_e32 v0, 0xffff0000, v42
	v_add_f32_e32 v1, v61, v1
	v_mul_f32_e32 v14, v1, v0
	v_lshlrev_b32_e32 v0, 16, v43
	v_add_f32_e32 v1, v61, v2
	v_mul_f32_e32 v15, v1, v0
	v_and_b32_e32 v0, 0xffff0000, v43
	v_add_f32_e32 v1, v61, v3
	v_mul_f32_e32 v3, v1, v0
	v_mul_f32_e32 v0, v14, v14
	v_mul_f32_e32 v1, v3, v3
	v_fmac_f32_e32 v0, v13, v13
	v_fmac_f32_e32 v1, v15, v15
	v_add_f32_e32 v0, v0, v1
	v_add_f32_e32 v2, v10, v0
	v_cndmask_b32_e32 v0, v167, v168, vcc
	v_lshlrev_b32_e32 v0, 2, v0
	ds_bpermute_b32 v10, v0, v2
	global_store_dwordx2 v[6:7], v[4:5], off offset:160
	v_cvt_pk_bf16_f32 v0, v8, v9
	v_cvt_pk_bf16_f32 v1, v11, v12
	v_cmp_lt_i32_e32 vcc, v170, v169
	global_store_dwordx2 v[6:7], v[0:1], off offset:192
	s_waitcnt lgkmcnt(0)
	v_add_f32_e32 v0, v2, v10
	v_cndmask_b32_e32 v1, v167, v170, vcc
	v_lshlrev_b32_e32 v1, 2, v1
	ds_bpermute_b32 v1, v1, v0
	v_cmp_eq_u32_e32 vcc, 0, v60
	v_cvt_pk_bf16_f32 v2, v13, v14
	v_cvt_pk_bf16_f32 v3, v15, v3
	global_store_dwordx2 v[6:7], v[2:3], off offset:224
	s_and_saveexec_b64 s[2:3], vcc
	s_cbranch_execz .LBB0_602
	s_waitcnt lgkmcnt(0)
	v_add_f32_e32 v2, v0, v1
	v_lshl_add_u64 v[0:1], v[40:41], 3, s[28:29]
	v_add_co_u32_e32 v0, vcc, 0x40000, v0
	s_nop 1
	v_addc_co_u32_e32 v1, vcc, 0, v1, vcc
	global_atomic_add_f32 v[0:1], v2, off offset:4
